# v22 + final LN next-row prefetch (double-buffered row registers)
# baseline (speedup 1.0000x reference)
; __device__ __forceinline__ void ln_row(const float* xin, float* yout, bf16_t* ybf, const float* g, const float* b, int lane) {
;     const f32x4* xr = (const f32x4*)xin + lane;
;     f32x4 v[8]; float s = 0.f;
; #pragma unroll
;     for (int j = 0; j < 8; ++j) { v[j] = xr[64 * j]; s += (v[j][0] + v[j][1]) + (v[j][2] + v[j][3]); }
;     const float mean = wave_sum(s, lane) * (1.f / DM); float s2 = 0.f;
; __global__ void __launch_bounds__(NWAVES * 64, 2) mega_fwd(Params P) {
;     ...
;     { PH_IDS
;       for (int m = gw; m < TOK; m += NGW) ln_row(H + (size_t)m * DM, H + (size_t)m * DM, (bf16_t*)nullptr, P.in[21] + (NLAYER - 1) * DM, P.in[22] + (NLAYER - 1) * DM, lane); }
.LBB0_1296:
	v_readlane_b32 s0, v255, 8
	v_readlane_b32 s1, v255, 9
	s_and_b64 vcc, exec, s[0:1]
	v_mbcnt_lo_u32_b32 v0, -1, 0
	v_mbcnt_hi_u32_b32 v0, -1, v0
	s_cbranch_vccnz .LBB0_1299
	v_ashrrev_i32_e32 v1, 31, v0
	v_lshlrev_b32_e32 v2, 2, v0
	v_lshlrev_b64 v[0:1], 4, v[0:1]
	v_xor_b32_e32 v56, 4, v2
	v_xor_b32_e32 v57, 8, v2
	v_xor_b32_e32 v58, 16, v2
	v_xor_b32_e32 v59, 32, v2
	v_xor_b32_e32 v60, 64, v2
	v_xor_b32_e32 v61, 0x80, v2
	v_lshl_add_u64 v[2:3], s[90:91], 0, v[0:1]
	s_mov_b64 s[0:1], 0x2000
	v_lshl_add_u64 v[4:5], s[92:93], 0, v[0:1]
	v_lshl_add_u64 v[32:33], v[2:3], 0, s[0:1]
	v_lshl_add_u64 v[34:35], v[4:5], 0, s[0:1]
	s_mov_b64 s[0:1], 0x3000
	v_lshl_add_u64 v[36:37], v[2:3], 0, s[0:1]
	v_lshl_add_u64 v[38:39], v[4:5], 0, s[0:1]
	s_mov_b64 s[0:1], 0x3400
	v_lshl_add_u64 v[40:41], v[2:3], 0, s[0:1]
	v_lshl_add_u64 v[42:43], v[4:5], 0, s[0:1]
	s_mov_b64 s[0:1], 0x3800
	v_lshl_add_u64 v[44:45], v[2:3], 0, s[0:1]
	v_lshl_add_u64 v[46:47], v[4:5], 0, s[0:1]
	s_mov_b64 s[0:1], 0x3c00
	v_lshl_add_u64 v[48:49], v[2:3], 0, s[0:1]
	v_lshl_add_u64 v[50:51], v[4:5], 0, s[0:1]
	s_add_i32 s4, s18, 0xfffff800
	s_lshl_b64 s[0:1], s[18:19], 13
	s_add_u32 s0, s94, s0
	s_addc_u32 s1, s95, s1
	v_lshl_add_u64 v[0:1], s[0:1], 0, v[0:1]
	s_mov_b64 s[0:1], 0x1c00
	v_lshl_add_u64 v[52:53], v[0:1], 0, s[0:1]
	v_mov_b32_e32 v62, 0x3727c5ac
	s_mov_b32 s5, 0xf800000
	v_mov_b32_e32 v63, 0x260
	s_mov_b64 s[2:3], 0x1000000
	global_load_dwordx4 v[100:103], v[32:33], off
	global_load_dwordx4 v[104:107], v[32:33], off offset:1024
	global_load_dwordx4 v[108:111], v[32:33], off offset:2048
	global_load_dwordx4 v[112:115], v[32:33], off offset:3072
	global_load_dwordx4 v[116:119], v[36:37], off
	global_load_dwordx4 v[120:123], v[40:41], off
	global_load_dwordx4 v[124:127], v[44:45], off
	global_load_dwordx4 v[128:131], v[48:49], off
	global_load_dwordx4 v[132:135], v[34:35], off
	global_load_dwordx4 v[136:139], v[34:35], off offset:1024
	global_load_dwordx4 v[140:143], v[34:35], off offset:2048
	global_load_dwordx4 v[144:147], v[34:35], off offset:3072
	global_load_dwordx4 v[148:151], v[38:39], off
	global_load_dwordx4 v[152:155], v[42:43], off
	global_load_dwordx4 v[156:159], v[46:47], off
	global_load_dwordx4 v[160:163], v[50:51], off
	s_waitcnt vmcnt(0)
	global_load_dwordx4 v[8:11], v[52:53], off offset:-3072
	global_load_dwordx4 v[12:15], v[52:53], off offset:-2048
	global_load_dwordx4 v[4:7], v[52:53], off offset:-1024
	v_add_co_u32_e32 v54, vcc, 0xfffff000, v52
	global_load_dwordx4 v[0:3], v[52:53], off
	s_nop 0
	v_addc_co_u32_e32 v55, vcc, -1, v53, vcc
	global_load_dwordx4 v[28:31], v[54:55], off offset:-3072
	global_load_dwordx4 v[24:27], v[54:55], off offset:-2048
	global_load_dwordx4 v[20:23], v[54:55], off offset:-1024
	global_load_dwordx4 v[16:19], v[52:53], off offset:-4096
	s_waitcnt vmcnt(0)
.LBB0_1298:
	s_addk_i32 s4, 0x800
	s_cmpk_gt_i32 s4, 0x77ff
	s_cselect_b32 s6, 0, s2
	s_cselect_b32 s7, 0, s3
	v_lshl_add_u64 v[196:197], v[52:53], 0, s[6:7]
	v_add_co_u32_e32 v198, vcc, 0xfffff000, v196
	s_nop 1
	v_addc_co_u32_e32 v199, vcc, -1, v197, vcc
	global_load_dwordx4 v[172:175], v[196:197], off offset:-3072
	global_load_dwordx4 v[176:179], v[196:197], off offset:-2048
	global_load_dwordx4 v[168:171], v[196:197], off offset:-1024
	global_load_dwordx4 v[164:167], v[196:197], off
	global_load_dwordx4 v[192:195], v[198:199], off offset:-3072
	global_load_dwordx4 v[188:191], v[198:199], off offset:-2048
	global_load_dwordx4 v[184:187], v[198:199], off offset:-1024
	global_load_dwordx4 v[180:183], v[196:197], off offset:-4096
	v_mov_b32_e32 v67, v10
	v_mov_b32_e32 v70, v13
	v_mov_b32_e32 v71, v14
	v_mov_b32_e32 v72, v12
	v_mov_b32_e32 v73, v15
	v_add_f32_e32 v74, v4, v5
	v_add_f32_e32 v76, v6, v7
	v_mov_b32_e32 v75, v2
	v_mov_b32_e32 v77, v3
	v_pk_add_f32 v[70:71], v[70:71], v[72:73]
	v_pk_add_f32 v[72:73], v[74:75], v[76:77]
	v_mov_b32_e32 v74, v28
	v_mov_b32_e32 v75, v24
	v_mov_b32_e32 v76, v29
	v_mov_b32_e32 v77, v25
	v_mov_b32_e32 v78, v30
	v_mov_b32_e32 v79, v26
	v_mov_b32_e32 v80, v31
	v_mov_b32_e32 v81, v27
	v_mov_b32_e32 v69, v11
	v_mov_b32_e32 v82, v21
	v_mov_b32_e32 v83, v22
	v_mov_b32_e32 v84, v20
	v_mov_b32_e32 v85, v23
	v_add_f32_e32 v66, v16, v17
	v_add_f32_e32 v68, v18, v19
	v_pk_add_f32 v[74:75], v[74:75], v[76:77]
	v_pk_add_f32 v[76:77], v[78:79], v[80:81]
	v_pk_add_f32 v[78:79], v[82:83], v[84:85]
	v_pk_add_f32 v[66:67], v[66:67], v[68:69]
	v_pk_add_f32 v[68:69], v[74:75], v[76:77]
	v_pk_add_f32 v[74:75], v[78:79], v[78:79] op_sel:[0,1] op_sel_hi:[1,0]
	v_add_f32_e32 v64, 0, v68
	v_mov_b32_e32 v65, v8
	v_mov_b32_e32 v75, v9
	v_add_f32_e32 v64, v64, v69
	v_pk_add_f32 v[64:65], v[64:65], v[74:75]
	v_pk_add_f32 v[70:71], v[70:71], v[70:71] op_sel:[0,1] op_sel_hi:[1,0]
	v_pk_add_f32 v[64:65], v[64:65], v[66:67]
	v_mov_b32_e32 v71, v1
	v_pk_add_f32 v[64:65], v[64:65], v[64:65] op_sel:[0,1] op_sel_hi:[1,0]
	s_nop 0
	v_mov_b32_e32 v65, v0
	v_pk_add_f32 v[64:65], v[64:65], v[70:71]
	s_nop 0
	v_pk_add_f32 v[64:65], v[64:65], v[72:73]
	s_nop 0
	v_add_f32_e32 v64, v64, v65
	ds_bpermute_b32 v65, v56, v64
	s_waitcnt lgkmcnt(0)
	v_add_f32_e32 v64, v64, v65
	ds_bpermute_b32 v65, v57, v64
	s_waitcnt lgkmcnt(0)
	v_add_f32_e32 v64, v64, v65
	ds_bpermute_b32 v65, v58, v64
	s_waitcnt lgkmcnt(0)
	v_add_f32_e32 v64, v64, v65
	ds_bpermute_b32 v65, v59, v64
	s_waitcnt lgkmcnt(0)
	v_add_f32_e32 v64, v64, v65
	ds_bpermute_b32 v65, v60, v64
	s_waitcnt lgkmcnt(0)
	v_add_f32_e32 v64, v64, v65
	ds_bpermute_b32 v65, v61, v64
	s_waitcnt lgkmcnt(0)
; __device__ __forceinline__ void ln_row(const float* xin, float* yout, bf16_t* ybf, const float* g, const float* b, int lane) {
;     ...
; #pragma unroll
;     for (int j = 0; j < 8; ++j) { v[j] = v[j] - mean; s2 += (v[j][0] * v[j][0] + v[j][1] * v[j][1]) + (v[j][2] * v[j][2] + v[j][3] * v[j][3]); }
;     const float rstd = 1.f / sqrtf(wave_sum(s2, lane) * (1.f / DM) + LN_EPS);
	v_add_f32_e32 v87, v64, v65
	v_fmamk_f32 v31, v87, 0xba000000, v31
	v_fmamk_f32 v29, v87, 0xba000000, v29
	v_fmamk_f32 v27, v87, 0xba000000, v27
	v_fmamk_f32 v25, v87, 0xba000000, v25
	v_fmamk_f32 v30, v87, 0xba000000, v30
	v_fmac_f32_e32 v28, 0xba000000, v87
	v_fmamk_f32 v26, v87, 0xba000000, v26
	v_fmac_f32_e32 v24, 0xba000000, v87
	v_fmamk_f32 v21, v87, 0xba000000, v21
	v_fmamk_f32 v20, v87, 0xba000000, v20
	v_fmamk_f32 v23, v87, 0xba000000, v23
	v_fmac_f32_e32 v22, 0xba000000, v87
	v_mov_b32_e32 v66, v29
	v_mov_b32_e32 v67, v25
	v_mov_b32_e32 v70, v31
	v_mov_b32_e32 v71, v27
	v_mov_b32_e32 v64, v28
	v_mov_b32_e32 v65, v24
	v_mov_b32_e32 v68, v30
	v_mov_b32_e32 v69, v26
	v_pk_mul_f32 v[72:73], v[22:23], v[22:23]
	v_pk_mul_f32 v[74:75], v[20:21], v[20:21]
	v_pk_mul_f32 v[66:67], v[66:67], v[66:67]
	v_pk_mul_f32 v[70:71], v[70:71], v[70:71]
	v_fmamk_f32 v16, v87, 0xba000000, v16
	v_fmac_f32_e32 v18, 0xba000000, v87
	v_pk_mov_b32 v[88:89], v[74:75], v[72:73] op_sel:[1,0]
	v_mov_b32_e32 v75, v73
	v_pk_fma_f32 v[64:65], v[64:65], v[64:65], v[66:67]
	v_pk_fma_f32 v[66:67], v[68:69], v[68:69], v[70:71]
	v_fmamk_f32 v17, v87, 0xba000000, v17
	v_fmamk_f32 v19, v87, 0xba000000, v19
	v_mul_f32_e32 v76, v16, v16
	v_mul_f32_e32 v78, v18, v18
	v_pk_add_f32 v[68:69], v[88:89], v[74:75]
	v_pk_add_f32 v[64:65], v[64:65], v[66:67]
	v_fmamk_f32 v11, v87, 0xba000000, v11
	v_fmamk_f32 v10, v87, 0xba000000, v10
	v_fmamk_f32 v9, v87, 0xba000000, v9
	v_fmac_f32_e32 v8, 0xba000000, v87
	v_fmamk_f32 v13, v87, 0xba000000, v13
	v_fmamk_f32 v12, v87, 0xba000000, v12
	v_fmamk_f32 v15, v87, 0xba000000, v15
	v_fmac_f32_e32 v14, 0xba000000, v87
	v_pk_fma_f32 v[72:73], v[16:17], v[16:17], v[76:77] op_sel_hi:[1,1,0]
	v_pk_fma_f32 v[76:77], v[18:19], v[18:19], v[78:79] op_sel_hi:[1,1,0]
	v_pk_add_f32 v[66:67], v[68:69], v[68:69] op_sel_hi:[0,1]
	v_pk_add_f32 v[64:65], v[64:65], v[64:65] op_sel_hi:[0,1]
	v_pk_mul_f32 v[80:81], v[14:15], v[14:15]
	v_pk_mul_f32 v[82:83], v[12:13], v[12:13]
	v_mul_f32_e32 v72, v8, v8
	v_mul_f32_e32 v76, v9, v9
	v_mul_f32_e32 v66, v10, v10
	v_mul_f32_e32 v64, v11, v11
	v_pk_mov_b32 v[78:79], v[82:83], v[80:81] op_sel:[1,0]
	v_mov_b32_e32 v83, v81
	v_pk_add_f32 v[68:69], v[72:73], v[76:77]
	v_pk_add_f32 v[64:65], v[66:67], v[64:65]
	v_pk_add_f32 v[70:71], v[78:79], v[82:83]
	v_pk_add_f32 v[64:65], v[68:69], v[64:65]
	v_pk_add_f32 v[72:73], v[70:71], v[70:71] op_sel_hi:[0,1]
	v_pk_add_f32 v[74:75], v[64:65], v[64:65] op_sel_hi:[0,1]
	v_fmamk_f32 v4, v87, 0xba000000, v4
	v_fmac_f32_e32 v6, 0xba000000, v87
	v_fmamk_f32 v5, v87, 0xba000000, v5
	v_fmamk_f32 v7, v87, 0xba000000, v7
	v_mul_f32_e32 v84, v4, v4
	v_mul_f32_e32 v86, v6, v6
	v_pk_fma_f32 v[80:81], v[4:5], v[4:5], v[84:85] op_sel_hi:[1, 1, 0]
	v_pk_fma_f32 v[84:85], v[6:7], v[6:7], v[86:87] op_sel_hi:[1, 1, 0]
	v_fmamk_f32 v77, v87, 0xba000000, v3
	v_fmamk_f32 v76, v87, 0xba000000, v2
	v_fmamk_f32 v1, v87, 0xba000000, v1
	v_fmac_f32_e32 v0, 0xba000000, v87
	v_mul_f32_e32 v80, v0, v0
	v_mul_f32_e32 v84, v1, v1
	v_mul_f32_e32 v72, v76, v76
	v_mul_f32_e32 v74, v77, v77
	v_pk_add_f32 v[2:3], v[80:81], v[84:85]
	v_pk_add_f32 v[72:73], v[72:73], v[74:75]
	s_nop 0
	v_pk_add_f32 v[2:3], v[2:3], v[72:73]
	s_nop 0
	v_add_f32_e32 v2, v2, v3
	ds_bpermute_b32 v3, v56, v2
	s_waitcnt lgkmcnt(0)
	v_add_f32_e32 v2, v2, v3
	ds_bpermute_b32 v3, v57, v2
	s_waitcnt lgkmcnt(0)
	v_add_f32_e32 v2, v2, v3
	ds_bpermute_b32 v3, v58, v2
	s_waitcnt lgkmcnt(0)
	v_add_f32_e32 v2, v2, v3
	ds_bpermute_b32 v3, v59, v2
	s_waitcnt lgkmcnt(0)
	v_add_f32_e32 v2, v2, v3
	ds_bpermute_b32 v3, v60, v2
	s_waitcnt lgkmcnt(0)
	v_add_f32_e32 v2, v2, v3
	ds_bpermute_b32 v3, v61, v2
	s_waitcnt lgkmcnt(0)
; __device__ __forceinline__ unsigned pk2(float lo, float hi) { return f2bf(lo) | (f2bf(hi) << 16); }
; __device__ __forceinline__ void ln_row(const float* xin, float* yout, bf16_t* ybf, const float* g, const float* b, int lane) {
;     ...
;     const float rstd = 1.f / sqrtf(wave_sum(s2, lane) * (1.f / DM) + LN_EPS);
;     f32x4* yo = (f32x4*)yout + lane; u32x2* o8 = (u32x2*)ybf + lane;
; #pragma unroll
;     for (int j = 0; j < 8; ++j) { const f32x4 gg = ((const f32x4*)g)[lane + 64 * j], bb = ((const f32x4*)b)[lane + 64 * j];
;         const f32x4 y = v[j] * rstd * gg + bb; yo[64 * j] = y; if (ybf) { u32x2 w; w.x = pk2(y[0], y[1]); w.y = pk2(y[2], y[3]); o8[64 * j] = w; } }
	v_add_f32_e32 v2, v2, v3
	v_fmamk_f32 v2, v2, 0x3a000000, v62
	v_mul_f32_e32 v3, 0x4f800000, v2
	v_cmp_gt_f32_e32 vcc, s5, v2
	s_nop 1
	v_cndmask_b32_e32 v2, v2, v3, vcc
	v_sqrt_f32_e32 v3, v2
	s_nop 0
	v_add_u32_e32 v72, -1, v3
	v_add_u32_e32 v73, 1, v3
	v_fma_f32 v74, -v72, v3, v2
	v_fma_f32 v75, -v73, v3, v2
	v_cmp_ge_f32_e64 s[0:1], 0, v74
	s_nop 1
	v_cndmask_b32_e64 v3, v3, v72, s[0:1]
	v_cmp_lt_f32_e64 s[0:1], 0, v75
	s_nop 1
	v_cndmask_b32_e64 v3, v3, v73, s[0:1]
	v_mul_f32_e32 v72, 0x37800000, v3
	v_cndmask_b32_e32 v3, v3, v72, vcc
	v_cmp_class_f32_e32 vcc, v2, v63
	s_nop 1
	v_cndmask_b32_e32 v2, v3, v2, vcc
	v_div_scale_f32 v3, s[0:1], v2, v2, 1.0
	v_rcp_f32_e32 v72, v3
	v_div_scale_f32 v73, vcc, 1.0, v2, 1.0
	v_fma_f32 v74, -v3, v72, 1.0
	v_fmac_f32_e32 v72, v74, v72
	v_mul_f32_e32 v74, v73, v72
	v_fma_f32 v75, -v3, v74, v73
	v_fmac_f32_e32 v74, v75, v72
	v_fma_f32 v3, -v3, v74, v73
	v_div_fmas_f32 v3, v3, v72, v74
	v_div_fixup_f32 v72, v3, v2, 1.0
	v_pk_mul_f32 v[2:3], v[28:29], v[72:73] op_sel_hi:[1, 0]
	v_pk_mul_f32 v[28:29], v[30:31], v[72:73] op_sel_hi:[1, 0]
	v_pk_mul_f32 v[24:25], v[24:25], v[72:73] op_sel_hi:[1, 0]
	v_pk_fma_f32 v[30:31], v[102:103], v[28:29], v[134:135]
	v_pk_fma_f32 v[28:29], v[100:101], v[2:3], v[132:133]
	global_store_dwordx4 v[54:55], v[28:31], off offset:-3072
	s_nop 1
	s_nop 0
	v_pk_mul_f32 v[2:3], v[26:27], v[72:73] op_sel_hi:[1, 0]
	v_pk_mul_f32 v[20:21], v[20:21], v[72:73] op_sel_hi:[1, 0]
	v_pk_mul_f32 v[16:17], v[16:17], v[72:73] op_sel_hi:[1, 0]
	v_pk_mul_f32 v[8:9], v[8:9], v[72:73] op_sel_hi:[1, 0]
	v_pk_mul_f32 v[12:13], v[12:13], v[72:73] op_sel_hi:[1, 0]
	v_pk_mul_f32 v[6:7], v[6:7], v[72:73] op_sel_hi:[1, 0]
	v_pk_mul_f32 v[0:1], v[0:1], v[72:73] op_sel_hi:[1, 0]
	v_pk_fma_f32 v[24:25], v[104:105], v[24:25], v[136:137]
	v_pk_fma_f32 v[26:27], v[106:107], v[2:3], v[138:139]
	global_store_dwordx4 v[54:55], v[24:27], off offset:-2048
	s_nop 1
	s_nop 0
	v_pk_mul_f32 v[2:3], v[22:23], v[72:73] op_sel_hi:[1, 0]
	v_pk_fma_f32 v[20:21], v[108:109], v[20:21], v[140:141]
	v_pk_fma_f32 v[22:23], v[110:111], v[2:3], v[142:143]
	global_store_dwordx4 v[54:55], v[20:23], off offset:-1024
	s_nop 1
	s_nop 0
	v_pk_mul_f32 v[2:3], v[18:19], v[72:73] op_sel_hi:[1, 0]
	v_pk_fma_f32 v[16:17], v[112:113], v[16:17], v[144:145]
	v_pk_fma_f32 v[18:19], v[114:115], v[2:3], v[146:147]
	global_store_dwordx4 v[52:53], v[16:19], off offset:-4096
	s_nop 1
	s_nop 0
	v_pk_mul_f32 v[2:3], v[10:11], v[72:73] op_sel_hi:[1, 0]
	v_pk_fma_f32 v[8:9], v[116:117], v[8:9], v[148:149]
	v_pk_fma_f32 v[10:11], v[118:119], v[2:3], v[150:151]
	global_store_dwordx4 v[52:53], v[8:11], off offset:-3072
	s_nop 1
	s_nop 0
	v_pk_mul_f32 v[2:3], v[14:15], v[72:73] op_sel_hi:[1, 0]
	v_pk_fma_f32 v[8:9], v[120:121], v[12:13], v[152:153]
	v_pk_fma_f32 v[10:11], v[122:123], v[2:3], v[154:155]
	global_store_dwordx4 v[52:53], v[8:11], off offset:-2048
	s_nop 1
	s_nop 0
	v_pk_mul_f32 v[2:3], v[4:5], v[72:73] op_sel_hi:[1, 0]
	v_pk_fma_f32 v[4:5], v[126:127], v[6:7], v[158:159]
	v_pk_fma_f32 v[2:3], v[124:125], v[2:3], v[156:157]
	global_store_dwordx4 v[52:53], v[2:5], off offset:-1024
	s_nop 1
	s_nop 0
	v_pk_mul_f32 v[10:11], v[76:77], v[72:73] op_sel_hi:[1, 0]
	v_pk_fma_f32 v[0:1], v[128:129], v[0:1], v[160:161]
	v_pk_fma_f32 v[2:3], v[130:131], v[10:11], v[162:163]
	global_store_dwordx4 v[52:53], v[0:3], off
	s_nop 1
	s_waitcnt vmcnt(8)
	v_mov_b32_e32 v0, v164
	v_mov_b32_e32 v1, v165
	v_mov_b32_e32 v2, v166
	v_mov_b32_e32 v3, v167
	v_mov_b32_e32 v4, v168
	v_mov_b32_e32 v5, v169
	v_mov_b32_e32 v6, v170
	v_mov_b32_e32 v7, v171
	v_mov_b32_e32 v8, v172
	v_mov_b32_e32 v9, v173
	v_mov_b32_e32 v10, v174
	v_mov_b32_e32 v11, v175
	v_mov_b32_e32 v12, v176
	v_mov_b32_e32 v13, v177
	v_mov_b32_e32 v14, v178
	v_mov_b32_e32 v15, v179
	v_mov_b32_e32 v16, v180
	v_mov_b32_e32 v17, v181
	v_mov_b32_e32 v18, v182
	v_mov_b32_e32 v19, v183
	v_mov_b32_e32 v20, v184
	v_mov_b32_e32 v21, v185
	v_mov_b32_e32 v22, v186
	v_mov_b32_e32 v23, v187
	v_mov_b32_e32 v24, v188
	v_mov_b32_e32 v25, v189
	v_mov_b32_e32 v26, v190
	v_mov_b32_e32 v27, v191
	v_mov_b32_e32 v28, v192
	v_mov_b32_e32 v29, v193
	v_mov_b32_e32 v30, v194
	v_mov_b32_e32 v31, v195
	v_mov_b32_e32 v52, v196
	v_mov_b32_e32 v53, v197
	v_mov_b32_e32 v54, v198
	v_mov_b32_e32 v55, v199
	s_cbranch_scc0 .LBB0_1298
